# in-projection mainloop replaced by the hand-written LDS-DMA ring loop (compiler epilogue kept)
# speedup vs baseline: 1.1114x; 1.0107x over previous
; __device__ __forceinline__ int otid() { int t = threadIdx.x; asm volatile("" : "+v"(t)); return t; }
; template <int NI> ...
;     ...
;   const int lane = tid & 63, wid = tid >> 6, wr = wid >> 1, wc = wid & 1;
;   const int lrow = tid >> 2, lch = (tid & 3) * 8;
;   const int l15 = lane & 15, lq = lane >> 4;
;   const bf16_t* pa = A + (size_t)lrow * lda + lch;
;   const bf16_t* pb = B + (size_t)lrow * ldb + lch;
;   const size_t a64 = (size_t)64 * lda, b64 = (size_t)64 * ldb;
;   u32x4 a0[2], a1[2], b0[NB], b1[NB];
;   const int nk = K >> 5;
;   const int klast = K - 32;
;   const int wofs = lrow * GROW + lch;
;   const int raofs = (wr * 64 + l15) * GROW + lq * 8;
;   const int rbofs = 128 * GROW + (wc * (16 * NI) + l15) * GROW + lq * 8;
;     ...
;   G_LOAD(a0, b0, 0);
;   G_LOAD(a1, b1, 32);
;   __syncthreads();
;   G_WRITE(a0, b0, 0);
;   __syncthreads();
; __device__ void phase_inproj(CParams& p, int l, int tm, int tn, char* smem) {
;   const int tid = otid();
;   bf16_t* sA = (bf16_t*)smem;
;   bf16_t* sB = sA + 128 * LDSS;
;   const bool lat = tm < 128;
;   const int tbase = lat ? ((tm >> 6) * 8192 + (tm & 63)) : tm * 128;
;   const int tstr = lat ? 64 : 1;
;   f32x4 acc[4][4];
;   zero_acc<4>(acc);
;   gemm_mainloop<4>(p.hbuf + (size_t)tbase * DM, DM * tstr, p.WinT + ((size_t)l * 1280 + tn * 128) * 1024, 1024, 1024, sA, sB, acc, tid);
.LBB0_313:
	s_lshl_b32 s2, s28, 3
	s_or_b32 s2, s2, s73
	s_cmp_gt_u32 s2, 21
	v_readlane_b32 s0, v224, 11
	s_cselect_b64 s[6:7], -1, 0
	v_readlane_b32 s1, v224, 12
	s_or_b64 s[6:7], s[0:1], s[6:7]
	s_and_b64 vcc, exec, s[6:7]
	s_cbranch_vccnz .LBB0_312
	s_mul_i32 s2, s2, 6
	s_add_i32 s2, s2, s80
	s_cmpk_gt_i32 s2, 0x83
	s_cbranch_scc1 .LBB0_312
	s_lshl_b32 s29, s2, 7
	s_and_b32 s4, s29, 0xffffe000
	s_and_b32 s6, s2, 63
	s_or_b32 s4, s4, s6
	s_cmpk_lt_i32 s2, 0x80
	s_cselect_b64 s[44:45], -1, 0
	s_and_b64 s[6:7], s[44:45], exec
	s_cselect_b32 s42, s4, s29
	v_mov_b32_e32 v88, v147
	s_cselect_b32 s48, 0x800000, s87
	s_cselect_b32 s2, 16, 10
	s_ashr_i32 s43, s42, 31
	s_lshl_b64 s[6:7], s[42:43], 11
	v_ashrrev_i32_e32 v46, 2, v88
	v_lshlrev_b32_e32 v0, 3, v88
	v_ashrrev_i32_e32 v47, 31, v46
	s_add_u32 s6, s22, s6
	v_and_b32_e32 v48, 24, v0
	s_addc_u32 s7, s23, s7
	v_lshlrev_b64 v[0:1], s2, v[46:47]
	v_lshl_add_u64 v[0:1], v[0:1], 1, s[6:7]
	v_lshlrev_b32_e32 v144, 1, v48
	v_lshl_add_u64 v[80:81], v[0:1], 0, v[144:145]
	v_lshlrev_b64 v[0:1], 11, v[46:47]
	v_lshl_add_u64 v[0:1], s[24:25], 0, v[0:1]
	v_lshl_add_u64 v[82:83], v[0:1], 0, v[144:145]
	v_ashrrev_i32_e32 v47, 1, v88
	v_and_b32_e32 v90, 15, v88
	v_and_b32_e32 v87, 0xffffffc0, v47
	v_and_b32_e32 v86, 0x4f, v88
	v_lshrrev_b32_e32 v89, 1, v88
	s_add_u32 s12, s2, 1
	s_mov_b64 s[8:9], s[24:25]
	v_readfirstlane_b32 s0, v88
	v_and_b32_e32 v70, 63, v88
	s_nop 3
	s_lshr_b32 s4, s0, 6
	s_lshl_b32 s0, s4, 11
	v_lshrrev_b32_e32 v71, 2, v70
	v_and_b32_e32 v72, 3, v70
	v_lshrrev_b32_e32 v73, 4, v70
	v_sub_u32_e32 v73, 0, v73
	v_and_b32_e32 v73, 3, v73
	v_xor_b32_e32 v73, v72, v73
	v_lshlrev_b32_e32 v73, 4, v73
	s_lshl_b32 s10, s4, 5
	v_add_u32_e32 v71, s10, v71
	v_lshlrev_b32_e32 v64, s12, v71
	v_add_u32_e32 v64, v64, v73
	v_add_u32_e32 v72, 16, v71
	v_lshlrev_b32_e32 v65, s12, v72
	v_add_u32_e32 v65, v65, v73
	v_lshl_add_u32 v66, v71, 11, v73
	v_add_u32_e32 v67, 0x8000, v66
	v_and_b32_e32 v71, 15, v70
	v_lshrrev_b32_e32 v72, 2, v71
	v_sub_u32_e32 v72, 0, v72
	v_and_b32_e32 v72, 3, v72
	v_lshrrev_b32_e32 v73, 4, v70
	v_xor_b32_e32 v72, v73, v72
	v_lshlrev_b32_e32 v72, 4, v72
	s_lshr_b32 s10, s4, 1
	s_lshl_b32 s10, s10, 6
	v_add_u32_e32 v68, s10, v71
	v_lshl_add_u32 v68, v68, 6, v72
	s_and_b32 s10, s4, 1
	s_lshl_b32 s10, s10, 6
	v_add_u32_e32 v69, s10, v71
	v_lshl_add_u32 v69, v69, 6, v72
	v_add_u32_e32 v69, 0x2000, v69
	s_barrier
	s_add_u32 m0, s0, 0x0
	s_nop 0
	global_load_lds_dwordx4 v64, s[6:7]
	s_add_u32 m0, s0, 0x400
	s_nop 0
	global_load_lds_dwordx4 v65, s[6:7]
	s_add_u32 m0, s0, 0x2000
	s_nop 0
	global_load_lds_dwordx4 v66, s[8:9]
	s_add_u32 m0, s0, 0x2400
	s_nop 0
	global_load_lds_dwordx4 v67, s[8:9]
	s_add_u32 s6, s6, 64
	s_addc_u32 s7, s7, 0
	s_add_u32 s8, s8, 64
	s_addc_u32 s9, s9, 0
	s_add_u32 m0, s0, 0x4000
	s_nop 0
	global_load_lds_dwordx4 v64, s[6:7]
	s_add_u32 m0, s0, 0x4400
	s_nop 0
	global_load_lds_dwordx4 v65, s[6:7]
	s_add_u32 m0, s0, 0x6000
	s_nop 0
	global_load_lds_dwordx4 v66, s[8:9]
	s_add_u32 m0, s0, 0x6400
	s_nop 0
	global_load_lds_dwordx4 v67, s[8:9]
	s_add_u32 s6, s6, 64
	s_addc_u32 s7, s7, 0
	s_add_u32 s8, s8, 64
	s_addc_u32 s9, s9, 0
	s_add_u32 m0, s0, 0xa400
	s_nop 0
	global_load_lds_dwordx4 v64, s[6:7]
	s_add_u32 m0, s0, 0xa800
	s_nop 0
	global_load_lds_dwordx4 v65, s[6:7]
	s_add_u32 m0, s0, 0xc400
	s_nop 0
	global_load_lds_dwordx4 v66, s[8:9]
	s_add_u32 m0, s0, 0xc800
	s_nop 0
	global_load_lds_dwordx4 v67, s[8:9]
	s_add_u32 s6, s6, 64
	s_addc_u32 s7, s7, 0
	s_add_u32 s8, s8, 64
	s_addc_u32 s9, s9, 0
	s_add_u32 m0, s0, 0xe400
	s_nop 0
	global_load_lds_dwordx4 v64, s[6:7]
	s_add_u32 m0, s0, 0xe800
	s_nop 0
	global_load_lds_dwordx4 v65, s[6:7]
	s_add_u32 m0, s0, 0x10400
	s_nop 0
	global_load_lds_dwordx4 v66, s[8:9]
	s_add_u32 m0, s0, 0x10800
	s_nop 0
	global_load_lds_dwordx4 v67, s[8:9]
	s_add_u32 s6, s6, 64
	s_addc_u32 s7, s7, 0
	s_add_u32 s8, s8, 64
	s_addc_u32 s9, s9, 0
	v_mov_b32_e32 v0, 0
	v_mov_b32_e32 v1, 0
	v_mov_b32_e32 v2, 0
	v_mov_b32_e32 v3, 0
	v_mov_b32_e32 v4, 0
	v_mov_b32_e32 v5, 0
	v_mov_b32_e32 v6, 0
	v_mov_b32_e32 v7, 0
	v_mov_b32_e32 v8, 0
	v_mov_b32_e32 v9, 0
	v_mov_b32_e32 v10, 0
	v_mov_b32_e32 v11, 0
	v_mov_b32_e32 v12, 0
	v_mov_b32_e32 v13, 0
	v_mov_b32_e32 v14, 0
	v_mov_b32_e32 v15, 0
	v_mov_b32_e32 v16, 0
	v_mov_b32_e32 v17, 0
	v_mov_b32_e32 v18, 0
	v_mov_b32_e32 v19, 0
	v_mov_b32_e32 v20, 0
	v_mov_b32_e32 v21, 0
	v_mov_b32_e32 v22, 0
	v_mov_b32_e32 v23, 0
	v_mov_b32_e32 v24, 0
	v_mov_b32_e32 v25, 0
	v_mov_b32_e32 v26, 0
	v_mov_b32_e32 v27, 0
	v_mov_b32_e32 v28, 0
	v_mov_b32_e32 v29, 0
	v_mov_b32_e32 v30, 0
	v_mov_b32_e32 v31, 0
	v_mov_b32_e32 v32, 0
	v_mov_b32_e32 v33, 0
	v_mov_b32_e32 v34, 0
	v_mov_b32_e32 v35, 0
	v_mov_b32_e32 v36, 0
	v_mov_b32_e32 v37, 0
	v_mov_b32_e32 v38, 0
	v_mov_b32_e32 v39, 0
	v_mov_b32_e32 v40, 0
	v_mov_b32_e32 v41, 0
	v_mov_b32_e32 v42, 0
	v_mov_b32_e32 v43, 0
	v_mov_b32_e32 v44, 0
	v_mov_b32_e32 v45, 0
	v_mov_b32_e32 v46, 0
	v_mov_b32_e32 v47, 0
	v_mov_b32_e32 v48, 0
	v_mov_b32_e32 v49, 0
	v_mov_b32_e32 v50, 0
	v_mov_b32_e32 v51, 0
	v_mov_b32_e32 v52, 0
	v_mov_b32_e32 v53, 0
	v_mov_b32_e32 v54, 0
	v_mov_b32_e32 v55, 0
	v_mov_b32_e32 v56, 0
	v_mov_b32_e32 v57, 0
	v_mov_b32_e32 v58, 0
	v_mov_b32_e32 v59, 0
	v_mov_b32_e32 v60, 0
	v_mov_b32_e32 v61, 0
	v_mov_b32_e32 v62, 0
	v_mov_b32_e32 v63, 0
	s_waitcnt vmcnt(12)
	s_barrier
	ds_read_b128 v[92:95], v68 offset:0
	ds_read_b128 v[108:111], v69 offset:0
	ds_read_b128 v[96:99], v68 offset:1024
	ds_read_b128 v[112:115], v69 offset:1024
	ds_read_b128 v[100:103], v68 offset:2048
	ds_read_b128 v[116:119], v69 offset:2048
	ds_read_b128 v[104:107], v68 offset:3072
	ds_read_b128 v[120:123], v69 offset:3072
	s_mov_b32 s1, 0
; template <int NI> ...
;     ...
;   for (int kt = 0; kt < nk; kt += 2) {
;     G_LOAD(a0, b0, min((kt + 2) * 32, klast));
;     G_COMPUTE(0);
;     G_WRITE(a1, b1, 1);
;     __syncthreads();
;     G_LOAD(a1, b1, min((kt + 3) * 32, klast));
;     G_COMPUTE(1);
;     G_WRITE(a0, b0, 0);
;     __syncthreads();
;   }
.Linp_kloop:
	s_waitcnt vmcnt(8) lgkmcnt(0)
	s_barrier
	s_add_u32 m0, s0, 0x0
	s_nop 0
	global_load_lds_dwordx4 v64, s[6:7]
	s_add_u32 m0, s0, 0x400
	s_nop 0
	global_load_lds_dwordx4 v65, s[6:7]
	s_add_u32 m0, s0, 0x2000
	s_nop 0
	global_load_lds_dwordx4 v66, s[8:9]
	s_add_u32 m0, s0, 0x2400
	s_nop 0
	global_load_lds_dwordx4 v67, s[8:9]
	s_add_u32 s6, s6, 64
	s_addc_u32 s7, s7, 0
	s_add_u32 s8, s8, 64
	s_addc_u32 s9, s9, 0
	v_mfma_f32_16x16x32_bf16 v[60:63], v[92:95], v[108:111], v[60:63]
	ds_read_b128 v[124:127], v68 offset:16384
	v_mfma_f32_16x16x32_bf16 v[56:59], v[92:95], v[112:115], v[56:59]
	ds_read_b128 v[140:143], v69 offset:16384
	v_mfma_f32_16x16x32_bf16 v[52:55], v[92:95], v[116:119], v[52:55]
	ds_read_b128 v[128:131], v68 offset:17408
	v_mfma_f32_16x16x32_bf16 v[48:51], v[92:95], v[120:123], v[48:51]
	ds_read_b128 v[148:151], v69 offset:17408
	v_mfma_f32_16x16x32_bf16 v[44:47], v[96:99], v[108:111], v[44:47]
	ds_read_b128 v[132:135], v68 offset:18432
	v_mfma_f32_16x16x32_bf16 v[40:43], v[96:99], v[112:115], v[40:43]
	ds_read_b128 v[152:155], v69 offset:18432
	v_mfma_f32_16x16x32_bf16 v[36:39], v[96:99], v[116:119], v[36:39]
	ds_read_b128 v[136:139], v68 offset:19456
	v_mfma_f32_16x16x32_bf16 v[32:35], v[96:99], v[120:123], v[32:35]
	ds_read_b128 v[156:159], v69 offset:19456
	v_mfma_f32_16x16x32_bf16 v[28:31], v[100:103], v[108:111], v[28:31]
	v_mfma_f32_16x16x32_bf16 v[24:27], v[100:103], v[112:115], v[24:27]
	v_mfma_f32_16x16x32_bf16 v[20:23], v[100:103], v[116:119], v[20:23]
	v_mfma_f32_16x16x32_bf16 v[16:19], v[100:103], v[120:123], v[16:19]
	v_mfma_f32_16x16x32_bf16 v[12:15], v[104:107], v[108:111], v[12:15]
	v_mfma_f32_16x16x32_bf16 v[4:7], v[104:107], v[112:115], v[4:7]
	v_mfma_f32_16x16x32_bf16 v[0:3], v[104:107], v[116:119], v[0:3]
	v_mfma_f32_16x16x32_bf16 v[8:11], v[104:107], v[120:123], v[8:11]
	s_waitcnt vmcnt(8) lgkmcnt(0)
	s_barrier
	s_add_u32 m0, s0, 0x4000
	s_nop 0
	global_load_lds_dwordx4 v64, s[6:7]
	s_add_u32 m0, s0, 0x4400
	s_nop 0
	global_load_lds_dwordx4 v65, s[6:7]
	s_add_u32 m0, s0, 0x6000
	s_nop 0
	global_load_lds_dwordx4 v66, s[8:9]
	s_add_u32 m0, s0, 0x6400
	s_nop 0
	global_load_lds_dwordx4 v67, s[8:9]
	s_add_u32 s6, s6, 64
	s_addc_u32 s7, s7, 0
	s_add_u32 s8, s8, 64
	s_addc_u32 s9, s9, 0
	v_mfma_f32_16x16x32_bf16 v[60:63], v[124:127], v[140:143], v[60:63]
	ds_read_b128 v[92:95], v68 offset:41984
	v_mfma_f32_16x16x32_bf16 v[56:59], v[124:127], v[148:151], v[56:59]
	ds_read_b128 v[108:111], v69 offset:41984
	v_mfma_f32_16x16x32_bf16 v[52:55], v[124:127], v[152:155], v[52:55]
	ds_read_b128 v[96:99], v68 offset:43008
	v_mfma_f32_16x16x32_bf16 v[48:51], v[124:127], v[156:159], v[48:51]
	ds_read_b128 v[112:115], v69 offset:43008
	v_mfma_f32_16x16x32_bf16 v[44:47], v[128:131], v[140:143], v[44:47]
	ds_read_b128 v[100:103], v68 offset:44032
	v_mfma_f32_16x16x32_bf16 v[40:43], v[128:131], v[148:151], v[40:43]
	ds_read_b128 v[116:119], v69 offset:44032
	v_mfma_f32_16x16x32_bf16 v[36:39], v[128:131], v[152:155], v[36:39]
	ds_read_b128 v[104:107], v68 offset:45056
	v_mfma_f32_16x16x32_bf16 v[32:35], v[128:131], v[156:159], v[32:35]
	ds_read_b128 v[120:123], v69 offset:45056
	v_mfma_f32_16x16x32_bf16 v[28:31], v[132:135], v[140:143], v[28:31]
	v_mfma_f32_16x16x32_bf16 v[24:27], v[132:135], v[148:151], v[24:27]
	v_mfma_f32_16x16x32_bf16 v[20:23], v[132:135], v[152:155], v[20:23]
	v_mfma_f32_16x16x32_bf16 v[16:19], v[132:135], v[156:159], v[16:19]
	v_mfma_f32_16x16x32_bf16 v[12:15], v[136:139], v[140:143], v[12:15]
	v_mfma_f32_16x16x32_bf16 v[4:7], v[136:139], v[148:151], v[4:7]
	v_mfma_f32_16x16x32_bf16 v[0:3], v[136:139], v[152:155], v[0:3]
	v_mfma_f32_16x16x32_bf16 v[8:11], v[136:139], v[156:159], v[8:11]
	s_waitcnt vmcnt(8) lgkmcnt(0)
	s_barrier
	s_add_u32 m0, s0, 0xa400
	s_nop 0
	global_load_lds_dwordx4 v64, s[6:7]
	s_add_u32 m0, s0, 0xa800
	s_nop 0
	global_load_lds_dwordx4 v65, s[6:7]
	s_add_u32 m0, s0, 0xc400
	s_nop 0
	global_load_lds_dwordx4 v66, s[8:9]
	s_add_u32 m0, s0, 0xc800
	s_nop 0
	global_load_lds_dwordx4 v67, s[8:9]
	s_add_u32 s6, s6, 64
	s_addc_u32 s7, s7, 0
	s_add_u32 s8, s8, 64
	s_addc_u32 s9, s9, 0
	v_mfma_f32_16x16x32_bf16 v[60:63], v[92:95], v[108:111], v[60:63]
	ds_read_b128 v[124:127], v68 offset:58368
	v_mfma_f32_16x16x32_bf16 v[56:59], v[92:95], v[112:115], v[56:59]
	ds_read_b128 v[140:143], v69 offset:58368
	v_mfma_f32_16x16x32_bf16 v[52:55], v[92:95], v[116:119], v[52:55]
	ds_read_b128 v[128:131], v68 offset:59392
	v_mfma_f32_16x16x32_bf16 v[48:51], v[92:95], v[120:123], v[48:51]
	ds_read_b128 v[148:151], v69 offset:59392
	v_mfma_f32_16x16x32_bf16 v[44:47], v[96:99], v[108:111], v[44:47]
	ds_read_b128 v[132:135], v68 offset:60416
	v_mfma_f32_16x16x32_bf16 v[40:43], v[96:99], v[112:115], v[40:43]
	ds_read_b128 v[152:155], v69 offset:60416
	v_mfma_f32_16x16x32_bf16 v[36:39], v[96:99], v[116:119], v[36:39]
	ds_read_b128 v[136:139], v68 offset:61440
	v_mfma_f32_16x16x32_bf16 v[32:35], v[96:99], v[120:123], v[32:35]
	ds_read_b128 v[156:159], v69 offset:61440
	v_mfma_f32_16x16x32_bf16 v[28:31], v[100:103], v[108:111], v[28:31]
	v_mfma_f32_16x16x32_bf16 v[24:27], v[100:103], v[112:115], v[24:27]
	v_mfma_f32_16x16x32_bf16 v[20:23], v[100:103], v[116:119], v[20:23]
	v_mfma_f32_16x16x32_bf16 v[16:19], v[100:103], v[120:123], v[16:19]
	v_mfma_f32_16x16x32_bf16 v[12:15], v[104:107], v[108:111], v[12:15]
	v_mfma_f32_16x16x32_bf16 v[4:7], v[104:107], v[112:115], v[4:7]
	v_mfma_f32_16x16x32_bf16 v[0:3], v[104:107], v[116:119], v[0:3]
	v_mfma_f32_16x16x32_bf16 v[8:11], v[104:107], v[120:123], v[8:11]
	s_waitcnt vmcnt(8) lgkmcnt(0)
	s_barrier
; __device__ __forceinline__ float sigmoidf_(float v) { return 1.f / (1.f + __expf(-v)); }
; template <int NI> ...
;     ...
;   for (int kt = 0; kt < nk; kt += 2) {
;     G_LOAD(a0, b0, min((kt + 2) * 32, klast));
;     G_COMPUTE(0);
;     G_WRITE(a1, b1, 1);
;     __syncthreads();
;     G_LOAD(a1, b1, min((kt + 3) * 32, klast));
;     G_COMPUTE(1);
;     G_WRITE(a0, b0, 0);
;     __syncthreads();
;   }
; __device__ void phase_inproj(CParams& p, int l, int tm, int tn, char* smem) {
;     ...
;     int T = tn - 6;
;     const int lane = tid & 63, wid = tid >> 6, wr = wid >> 1, wc = wid & 1;
; #pragma unroll
;     for (int mi = 0; mi < 4; mi++)
; #pragma unroll
;       for (int a = 0; a < 2; a++)
; #pragma unroll
;         for (int j = 0; j < 4; j++) {
;           int rl = wr * 64 + mi * 16 + (lane >> 4) * 4 + j;
;           int ch = T * 64 + wc * 32 + a * 16 + (lane & 15);
;           float val = acc[mi][2 * a][j], gt = acc[mi][2 * a + 1][j];
;           p.zv[(size_t)(tbase + rl * tstr) * 256 + ch] = val * sigmoidf_(gt);
;         }
	s_add_u32 m0, s0, 0xe400
	s_nop 0
	global_load_lds_dwordx4 v64, s[6:7]
	s_add_u32 m0, s0, 0xe800
	s_nop 0
	global_load_lds_dwordx4 v65, s[6:7]
	s_add_u32 m0, s0, 0x10400
	s_nop 0
	global_load_lds_dwordx4 v66, s[8:9]
	s_add_u32 m0, s0, 0x10800
	s_nop 0
	global_load_lds_dwordx4 v67, s[8:9]
	s_add_u32 s6, s6, 64
	s_addc_u32 s7, s7, 0
	s_add_u32 s8, s8, 64
	s_addc_u32 s9, s9, 0
	v_mfma_f32_16x16x32_bf16 v[60:63], v[124:127], v[140:143], v[60:63]
	ds_read_b128 v[92:95], v68 offset:0
	v_mfma_f32_16x16x32_bf16 v[56:59], v[124:127], v[148:151], v[56:59]
	ds_read_b128 v[108:111], v69 offset:0
	v_mfma_f32_16x16x32_bf16 v[52:55], v[124:127], v[152:155], v[52:55]
	ds_read_b128 v[96:99], v68 offset:1024
	v_mfma_f32_16x16x32_bf16 v[48:51], v[124:127], v[156:159], v[48:51]
	ds_read_b128 v[112:115], v69 offset:1024
	v_mfma_f32_16x16x32_bf16 v[44:47], v[128:131], v[140:143], v[44:47]
	ds_read_b128 v[100:103], v68 offset:2048
	v_mfma_f32_16x16x32_bf16 v[40:43], v[128:131], v[148:151], v[40:43]
	ds_read_b128 v[116:119], v69 offset:2048
	v_mfma_f32_16x16x32_bf16 v[36:39], v[128:131], v[152:155], v[36:39]
	ds_read_b128 v[104:107], v68 offset:3072
	v_mfma_f32_16x16x32_bf16 v[32:35], v[128:131], v[156:159], v[32:35]
	ds_read_b128 v[120:123], v69 offset:3072
	v_mfma_f32_16x16x32_bf16 v[28:31], v[132:135], v[140:143], v[28:31]
	v_mfma_f32_16x16x32_bf16 v[24:27], v[132:135], v[148:151], v[24:27]
	v_mfma_f32_16x16x32_bf16 v[20:23], v[132:135], v[152:155], v[20:23]
	v_mfma_f32_16x16x32_bf16 v[16:19], v[132:135], v[156:159], v[16:19]
	v_mfma_f32_16x16x32_bf16 v[12:15], v[136:139], v[140:143], v[12:15]
	v_mfma_f32_16x16x32_bf16 v[4:7], v[136:139], v[148:151], v[4:7]
	v_mfma_f32_16x16x32_bf16 v[0:3], v[136:139], v[152:155], v[0:3]
	v_mfma_f32_16x16x32_bf16 v[8:11], v[136:139], v[156:159], v[8:11]
	s_add_u32 s1, s1, 1
	s_cmp_lt_u32 s1, 8
	s_cbranch_scc1 .Linp_kloop
	s_waitcnt vmcnt(0) lgkmcnt(0)
	s_barrier
	s_movk_i32 s49, 0x400
	s_nop 15
	s_nop 15
	s_mov_b64 s[26:27], -1
	s_andn2_b64 vcc, exec, s[82:83]
	s_waitcnt vmcnt(1)
	v_lshrrev_b32_e32 v66, 2, v88
	s_cbranch_vccnz .LBB0_319
	v_mul_f32_e32 v64, 0xbfb8aa3b, v56
	v_exp_f32_e32 v64, v64
	s_load_dwordx2 s[6:7], s[20:21], 0x1a8
	v_readlane_b32 s2, v225, 44
	v_and_or_b32 v67, v66, 12, v87
	v_add_f32_e32 v68, 1.0, v64
	v_div_scale_f32 v69, s[8:9], v68, v68, 1.0
	v_rcp_f32_e32 v70, v69
	v_and_b32_e32 v64, 32, v89
	v_or3_b32 v144, v64, s2, v90
	s_waitcnt lgkmcnt(0)
	v_lshl_add_u64 v[64:65], v[144:145], 2, s[6:7]
	v_fma_f32 v71, -v69, v70, 1.0
	v_fmac_f32_e32 v70, v71, v70
	v_div_scale_f32 v71, vcc, 1.0, v68, 1.0
	v_mul_f32_e32 v72, v71, v70
	v_fma_f32 v73, -v69, v72, v71
	v_fmac_f32_e32 v72, v73, v70
	v_fma_f32 v69, -v69, v72, v71
	v_div_fmas_f32 v69, v69, v70, v72
	v_div_fixup_f32 v68, v69, v68, 1.0
	v_mul_f32_e32 v69, 0xbfb8aa3b, v57
	v_exp_f32_e32 v71, v69
	s_and_b64 s[6:7], s[44:45], exec
	s_cselect_b32 s4, 6, 0
	v_mul_f32_e32 v70, v60, v68
	v_add_f32_e32 v71, 1.0, v71
	v_div_scale_f32 v72, s[6:7], v71, v71, 1.0
	v_rcp_f32_e32 v73, v72
	v_lshlrev_b32_e32 v68, s4, v67
	v_add_u32_e32 v68, s42, v68
	v_ashrrev_i32_e32 v69, 31, v68
	v_fma_f32 v74, -v72, v73, 1.0
	v_fmac_f32_e32 v73, v74, v73
	v_div_scale_f32 v74, vcc, 1.0, v71, 1.0
	v_mul_f32_e32 v75, v74, v73
	s_waitcnt vmcnt(0)
	v_fma_f32 v76, -v72, v75, v74
	v_fmac_f32_e32 v75, v76, v73
	v_fma_f32 v72, -v72, v75, v74
	v_div_fmas_f32 v72, v72, v73, v75
	v_div_fixup_f32 v71, v72, v71, 1.0
	v_mul_f32_e32 v72, v61, v71
	v_mul_f32_e32 v71, 0xbfb8aa3b, v58
	v_exp_f32_e32 v73, v71
	v_lshlrev_b64 v[68:69], 10, v[68:69]
	v_lshl_add_u64 v[68:69], v[64:65], 0, v[68:69]
	global_store_dword v[68:69], v70, off
	v_add_f32_e32 v73, 1.0, v73
	v_div_scale_f32 v74, s[6:7], v73, v73, 1.0
	v_rcp_f32_e32 v75, v74
	v_or_b32_e32 v70, 1, v67
	v_lshlrev_b32_e32 v70, s4, v70
	v_add_u32_e32 v70, s42, v70
	v_fma_f32 v76, -v74, v75, 1.0
	v_fmac_f32_e32 v75, v76, v75
	v_div_scale_f32 v76, vcc, 1.0, v73, 1.0
	v_mul_f32_e32 v77, v76, v75
	v_fma_f32 v78, -v74, v77, v76
	v_fmac_f32_e32 v77, v78, v75
	v_fma_f32 v74, -v74, v77, v76
	v_div_fmas_f32 v74, v74, v75, v77
	v_div_fixup_f32 v73, v74, v73, 1.0
	v_mul_f32_e32 v74, v62, v73
	v_mul_f32_e32 v73, 0xbfb8aa3b, v59
	v_exp_f32_e32 v75, v73
	v_ashrrev_i32_e32 v71, 31, v70
	v_lshlrev_b64 v[70:71], 10, v[70:71]
	v_lshl_add_u64 v[70:71], v[64:65], 0, v[70:71]
	v_add_f32_e32 v75, 1.0, v75
	v_div_scale_f32 v76, s[6:7], v75, v75, 1.0
	v_rcp_f32_e32 v77, v76
	global_store_dword v[70:71], v72, off
	v_or_b32_e32 v72, 2, v67
	v_lshlrev_b32_e32 v72, s4, v72
	v_fma_f32 v78, -v76, v77, 1.0
	v_fmac_f32_e32 v77, v78, v77
	v_div_scale_f32 v78, vcc, 1.0, v75, 1.0
	v_mul_f32_e32 v79, v78, v77
	v_fma_f32 v80, -v76, v79, v78
	v_fmac_f32_e32 v79, v80, v77
	v_fma_f32 v76, -v76, v79, v78
	v_div_fmas_f32 v76, v76, v77, v79
	v_div_fixup_f32 v75, v76, v75, 1.0
	v_mul_f32_e32 v76, v63, v75
	v_mul_f32_e32 v75, 0xbfb8aa3b, v48
	v_add_u32_e32 v72, s42, v72
	v_exp_f32_e32 v77, v75
	v_ashrrev_i32_e32 v73, 31, v72
	v_lshlrev_b64 v[72:73], 10, v[72:73]
	v_lshl_add_u64 v[72:73], v[64:65], 0, v[72:73]
	global_store_dword v[72:73], v74, off
	v_or_b32_e32 v74, 3, v67
	v_add_f32_e32 v77, 1.0, v77
	v_lshlrev_b32_e32 v74, s4, v74
	v_div_scale_f32 v78, s[6:7], v77, v77, 1.0
	v_add_u32_e32 v74, s42, v74
	v_rcp_f32_e32 v79, v78
	v_ashrrev_i32_e32 v75, 31, v74
	v_lshlrev_b64 v[74:75], 10, v[74:75]
	v_lshl_add_u64 v[74:75], v[64:65], 0, v[74:75]
	global_store_dword v[74:75], v76, off
	v_fma_f32 v76, -v78, v79, 1.0
	v_fmac_f32_e32 v79, v76, v79
	v_div_scale_f32 v76, vcc, 1.0, v77, 1.0
	v_mul_f32_e32 v80, v76, v79
	v_fma_f32 v81, -v78, v80, v76
	v_fmac_f32_e32 v80, v81, v79
	v_mul_f32_e32 v81, 0xbfb8aa3b, v49
; __device__ __forceinline__ float sigmoidf_(float v) { return 1.f / (1.f + __expf(-v)); }
; __device__ void phase_inproj(CParams& p, int l, int tm, int tn, char* smem) {
;     ...
;     int T = tn - 6;
;     const int lane = tid & 63, wid = tid >> 6, wr = wid >> 1, wc = wid & 1;
; #pragma unroll
;     for (int mi = 0; mi < 4; mi++)
; #pragma unroll
;       for (int a = 0; a < 2; a++)
; #pragma unroll
;         for (int j = 0; j < 4; j++) {
;           int rl = wr * 64 + mi * 16 + (lane >> 4) * 4 + j;
;           int ch = T * 64 + wc * 32 + a * 16 + (lane & 15);
;           float val = acc[mi][2 * a][j], gt = acc[mi][2 * a + 1][j];
;           p.zv[(size_t)(tbase + rl * tstr) * 256 + ch] = val * sigmoidf_(gt);
;         }
	v_exp_f32_e32 v81, v81
	v_fma_f32 v76, -v78, v80, v76
	v_div_fmas_f32 v76, v76, v79, v80
	v_div_fixup_f32 v76, v76, v77, 1.0
	v_add_f32_e32 v78, 1.0, v81
	v_div_scale_f32 v79, s[6:7], v78, v78, 1.0
	v_rcp_f32_e32 v80, v79
	v_mul_f32_e32 v76, v52, v76
	global_store_dword v[68:69], v76, off offset:64
	s_mov_b64 s[26:27], 0
	v_fma_f32 v68, -v79, v80, 1.0
	v_fmac_f32_e32 v80, v68, v80
	v_div_scale_f32 v68, vcc, 1.0, v78, 1.0
	v_mul_f32_e32 v69, v68, v80
	v_fma_f32 v76, -v79, v69, v68
	v_fmac_f32_e32 v69, v76, v80
	v_mul_f32_e32 v76, 0xbfb8aa3b, v50
	v_exp_f32_e32 v76, v76
	v_fma_f32 v68, -v79, v69, v68
	v_div_fmas_f32 v68, v68, v80, v69
	v_div_fixup_f32 v68, v68, v78, 1.0
	v_add_f32_e32 v69, 1.0, v76
	v_div_scale_f32 v76, s[6:7], v69, v69, 1.0
	v_rcp_f32_e32 v77, v76
	v_mul_f32_e32 v68, v53, v68
	global_store_dword v[70:71], v68, off offset:64
	v_fma_f32 v68, -v76, v77, 1.0
	v_fmac_f32_e32 v77, v68, v77
	v_div_scale_f32 v68, vcc, 1.0, v69, 1.0
	v_mul_f32_e32 v70, v68, v77
	v_fma_f32 v71, -v76, v70, v68
	v_fmac_f32_e32 v70, v71, v77
	v_mul_f32_e32 v71, 0xbfb8aa3b, v51
	v_exp_f32_e32 v71, v71
	v_fma_f32 v68, -v76, v70, v68
	v_div_fmas_f32 v68, v68, v77, v70
	v_div_fixup_f32 v68, v68, v69, 1.0
	v_add_f32_e32 v70, 1.0, v71
	v_div_scale_f32 v71, s[6:7], v70, v70, 1.0
	v_rcp_f32_e32 v76, v71
	v_mul_f32_e32 v68, v54, v68
	global_store_dword v[72:73], v68, off offset:64
	v_fma_f32 v68, -v71, v76, 1.0
	v_fmac_f32_e32 v76, v68, v76
	v_div_scale_f32 v68, vcc, 1.0, v70, 1.0
	v_mul_f32_e32 v69, v68, v76
	v_fma_f32 v72, -v71, v69, v68
	v_fmac_f32_e32 v69, v72, v76
	v_fma_f32 v68, -v71, v69, v68
	v_mul_f32_e32 v71, 0xbfb8aa3b, v40
	v_exp_f32_e32 v71, v71
	v_div_fmas_f32 v68, v68, v76, v69
	v_div_fixup_f32 v68, v68, v70, 1.0
	v_mul_f32_e32 v68, v55, v68
	v_add_f32_e32 v69, 1.0, v71
	v_div_scale_f32 v70, s[6:7], v69, v69, 1.0
	v_rcp_f32_e32 v71, v70
	global_store_dword v[74:75], v68, off offset:64
	v_or_b32_e32 v68, 16, v67
	v_lshlrev_b32_e32 v68, s4, v68
	v_fma_f32 v72, -v70, v71, 1.0
	v_fmac_f32_e32 v71, v72, v71
	v_div_scale_f32 v72, vcc, 1.0, v69, 1.0
	v_mul_f32_e32 v73, v72, v71
	v_fma_f32 v74, -v70, v73, v72
	v_fmac_f32_e32 v73, v74, v71
	v_fma_f32 v70, -v70, v73, v72
	v_div_fmas_f32 v70, v70, v71, v73
	v_div_fixup_f32 v69, v70, v69, 1.0
	v_mul_f32_e32 v70, v44, v69
	v_mul_f32_e32 v69, 0xbfb8aa3b, v41
	v_exp_f32_e32 v71, v69
	v_add_u32_e32 v68, s42, v68
	v_ashrrev_i32_e32 v69, 31, v68
	v_lshlrev_b64 v[68:69], 10, v[68:69]
	v_add_f32_e32 v71, 1.0, v71
	v_div_scale_f32 v72, s[6:7], v71, v71, 1.0
	v_rcp_f32_e32 v73, v72
	v_lshl_add_u64 v[68:69], v[64:65], 0, v[68:69]
	global_store_dword v[68:69], v70, off
	v_or_b32_e32 v70, 17, v67
	v_fma_f32 v74, -v72, v73, 1.0
	v_fmac_f32_e32 v73, v74, v73
	v_div_scale_f32 v74, vcc, 1.0, v71, 1.0
	v_mul_f32_e32 v75, v74, v73
	v_fma_f32 v76, -v72, v75, v74
	v_fmac_f32_e32 v75, v76, v73
	v_fma_f32 v72, -v72, v75, v74
	v_div_fmas_f32 v72, v72, v73, v75
	v_div_fixup_f32 v71, v72, v71, 1.0
	v_mul_f32_e32 v72, v45, v71
	v_mul_f32_e32 v71, 0xbfb8aa3b, v42
	v_exp_f32_e32 v73, v71
	v_lshlrev_b32_e32 v70, s4, v70
	v_add_u32_e32 v70, s42, v70
	v_ashrrev_i32_e32 v71, 31, v70
	v_add_f32_e32 v73, 1.0, v73
	v_div_scale_f32 v74, s[6:7], v73, v73, 1.0
	v_rcp_f32_e32 v75, v74
	v_lshlrev_b64 v[70:71], 10, v[70:71]
	v_lshl_add_u64 v[70:71], v[64:65], 0, v[70:71]
	global_store_dword v[70:71], v72, off
	v_fma_f32 v76, -v74, v75, 1.0
	v_fmac_f32_e32 v75, v76, v75
	v_div_scale_f32 v76, vcc, 1.0, v73, 1.0
	v_mul_f32_e32 v77, v76, v75
	v_fma_f32 v78, -v74, v77, v76
	v_fmac_f32_e32 v77, v78, v75
	v_fma_f32 v74, -v74, v77, v76
	v_div_fmas_f32 v74, v74, v75, v77
	v_div_fixup_f32 v73, v74, v73, 1.0
	v_mul_f32_e32 v74, v46, v73
	v_mul_f32_e32 v73, 0xbfb8aa3b, v43
	v_exp_f32_e32 v75, v73
	v_or_b32_e32 v72, 18, v67
	v_lshlrev_b32_e32 v72, s4, v72
	v_add_u32_e32 v72, s42, v72
	v_add_f32_e32 v75, 1.0, v75
	v_div_scale_f32 v76, s[6:7], v75, v75, 1.0
	v_rcp_f32_e32 v77, v76
	v_ashrrev_i32_e32 v73, 31, v72
	v_lshlrev_b64 v[72:73], 10, v[72:73]
	v_lshl_add_u64 v[72:73], v[64:65], 0, v[72:73]
	v_fma_f32 v78, -v76, v77, 1.0
	v_fmac_f32_e32 v77, v78, v77
	v_div_scale_f32 v78, vcc, 1.0, v75, 1.0
	v_mul_f32_e32 v79, v78, v77
	v_fma_f32 v80, -v76, v79, v78
	v_fmac_f32_e32 v79, v80, v77
	v_fma_f32 v76, -v76, v79, v78
	v_div_fmas_f32 v76, v76, v77, v79
	v_div_fixup_f32 v75, v76, v75, 1.0
	v_mul_f32_e32 v76, v47, v75
	v_mul_f32_e32 v75, 0xbfb8aa3b, v32
	v_exp_f32_e32 v77, v75
	global_store_dword v[72:73], v74, off
	v_or_b32_e32 v74, 19, v67
	v_lshlrev_b32_e32 v74, s4, v74
	v_add_f32_e32 v77, 1.0, v77
	v_div_scale_f32 v78, s[6:7], v77, v77, 1.0
	v_add_u32_e32 v74, s42, v74
	v_rcp_f32_e32 v79, v78
	v_ashrrev_i32_e32 v75, 31, v74
	v_lshlrev_b64 v[74:75], 10, v[74:75]
	v_lshl_add_u64 v[74:75], v[64:65], 0, v[74:75]
	global_store_dword v[74:75], v76, off
	v_fma_f32 v76, -v78, v79, 1.0
	v_fmac_f32_e32 v79, v76, v79
	v_div_scale_f32 v76, vcc, 1.0, v77, 1.0
	v_mul_f32_e32 v80, v76, v79
	v_fma_f32 v81, -v78, v80, v76
	v_fmac_f32_e32 v80, v81, v79
	v_mul_f32_e32 v81, 0xbfb8aa3b, v33
	v_exp_f32_e32 v81, v81
	v_fma_f32 v76, -v78, v80, v76
	v_div_fmas_f32 v76, v76, v79, v80
	v_div_fixup_f32 v76, v76, v77, 1.0
	v_add_f32_e32 v78, 1.0, v81
	v_div_scale_f32 v79, s[6:7], v78, v78, 1.0
	v_rcp_f32_e32 v80, v79
	v_mul_f32_e32 v76, v36, v76
	global_store_dword v[68:69], v76, off offset:64
	v_fma_f32 v68, -v79, v80, 1.0
	v_fmac_f32_e32 v80, v68, v80
	v_div_scale_f32 v68, vcc, 1.0, v78, 1.0
	v_mul_f32_e32 v69, v68, v80
	v_fma_f32 v76, -v79, v69, v68
	v_fmac_f32_e32 v69, v76, v80
	v_mul_f32_e32 v76, 0xbfb8aa3b, v34
	v_exp_f32_e32 v76, v76
	v_fma_f32 v68, -v79, v69, v68
; __device__ __forceinline__ float sigmoidf_(float v) { return 1.f / (1.f + __expf(-v)); }
; __device__ void phase_inproj(CParams& p, int l, int tm, int tn, char* smem) {
;     ...
;     int T = tn - 6;
;     const int lane = tid & 63, wid = tid >> 6, wr = wid >> 1, wc = wid & 1;
; #pragma unroll
;     for (int mi = 0; mi < 4; mi++)
; #pragma unroll
;       for (int a = 0; a < 2; a++)
; #pragma unroll
;         for (int j = 0; j < 4; j++) {
;           int rl = wr * 64 + mi * 16 + (lane >> 4) * 4 + j;
;           int ch = T * 64 + wc * 32 + a * 16 + (lane & 15);
;           float val = acc[mi][2 * a][j], gt = acc[mi][2 * a + 1][j];
;           p.zv[(size_t)(tbase + rl * tstr) * 256 + ch] = val * sigmoidf_(gt);
;         }
	v_div_fmas_f32 v68, v68, v80, v69
	v_div_fixup_f32 v68, v68, v78, 1.0
	v_add_f32_e32 v69, 1.0, v76
	v_div_scale_f32 v76, s[6:7], v69, v69, 1.0
	v_rcp_f32_e32 v77, v76
	v_mul_f32_e32 v68, v37, v68
	global_store_dword v[70:71], v68, off offset:64
	v_fma_f32 v68, -v76, v77, 1.0
	v_fmac_f32_e32 v77, v68, v77
	v_div_scale_f32 v68, vcc, 1.0, v69, 1.0
	v_mul_f32_e32 v70, v68, v77
	v_fma_f32 v71, -v76, v70, v68
	v_fmac_f32_e32 v70, v71, v77
	v_mul_f32_e32 v71, 0xbfb8aa3b, v35
	v_exp_f32_e32 v71, v71
	v_fma_f32 v68, -v76, v70, v68
	v_div_fmas_f32 v68, v68, v77, v70
	v_div_fixup_f32 v68, v68, v69, 1.0
	v_add_f32_e32 v70, 1.0, v71
	v_div_scale_f32 v71, s[6:7], v70, v70, 1.0
	v_rcp_f32_e32 v76, v71
	v_mul_f32_e32 v68, v38, v68
	global_store_dword v[72:73], v68, off offset:64
	v_fma_f32 v68, -v71, v76, 1.0
	v_fmac_f32_e32 v76, v68, v76
	v_div_scale_f32 v68, vcc, 1.0, v70, 1.0
	v_mul_f32_e32 v69, v68, v76
	v_fma_f32 v72, -v71, v69, v68
	v_fmac_f32_e32 v69, v72, v76
	v_fma_f32 v68, -v71, v69, v68
	v_mul_f32_e32 v71, 0xbfb8aa3b, v24
	v_exp_f32_e32 v71, v71
	v_div_fmas_f32 v68, v68, v76, v69
	v_div_fixup_f32 v68, v68, v70, 1.0
	v_mul_f32_e32 v68, v39, v68
	v_add_f32_e32 v69, 1.0, v71
	v_div_scale_f32 v70, s[6:7], v69, v69, 1.0
	v_rcp_f32_e32 v71, v70
	global_store_dword v[74:75], v68, off offset:64
	v_or_b32_e32 v68, 32, v67
	v_lshlrev_b32_e32 v68, s4, v68
	v_fma_f32 v72, -v70, v71, 1.0
	v_fmac_f32_e32 v71, v72, v71
	v_div_scale_f32 v72, vcc, 1.0, v69, 1.0
	v_mul_f32_e32 v73, v72, v71
	v_fma_f32 v74, -v70, v73, v72
	v_fmac_f32_e32 v73, v74, v71
	v_fma_f32 v70, -v70, v73, v72
	v_div_fmas_f32 v70, v70, v71, v73
	v_div_fixup_f32 v69, v70, v69, 1.0
	v_mul_f32_e32 v70, v28, v69
	v_mul_f32_e32 v69, 0xbfb8aa3b, v25
	v_exp_f32_e32 v71, v69
	v_add_u32_e32 v68, s42, v68
	v_ashrrev_i32_e32 v69, 31, v68
	v_lshlrev_b64 v[68:69], 10, v[68:69]
	v_add_f32_e32 v71, 1.0, v71
	v_div_scale_f32 v72, s[6:7], v71, v71, 1.0
	v_rcp_f32_e32 v73, v72
	v_lshl_add_u64 v[68:69], v[64:65], 0, v[68:69]
	global_store_dword v[68:69], v70, off
	v_or_b32_e32 v70, 33, v67
	v_fma_f32 v74, -v72, v73, 1.0
	v_fmac_f32_e32 v73, v74, v73
	v_div_scale_f32 v74, vcc, 1.0, v71, 1.0
	v_mul_f32_e32 v75, v74, v73
	v_fma_f32 v76, -v72, v75, v74
	v_fmac_f32_e32 v75, v76, v73
	v_fma_f32 v72, -v72, v75, v74
	v_div_fmas_f32 v72, v72, v73, v75
	v_div_fixup_f32 v71, v72, v71, 1.0
	v_mul_f32_e32 v72, v29, v71
	v_mul_f32_e32 v71, 0xbfb8aa3b, v26
	v_exp_f32_e32 v73, v71
	v_lshlrev_b32_e32 v70, s4, v70
	v_add_u32_e32 v70, s42, v70
	v_ashrrev_i32_e32 v71, 31, v70
	v_add_f32_e32 v73, 1.0, v73
	v_div_scale_f32 v74, s[6:7], v73, v73, 1.0
	v_rcp_f32_e32 v75, v74
	v_lshlrev_b64 v[70:71], 10, v[70:71]
	v_lshl_add_u64 v[70:71], v[64:65], 0, v[70:71]
	global_store_dword v[70:71], v72, off
	v_fma_f32 v76, -v74, v75, 1.0
	v_fmac_f32_e32 v75, v76, v75
	v_div_scale_f32 v76, vcc, 1.0, v73, 1.0
	v_mul_f32_e32 v77, v76, v75
	v_fma_f32 v78, -v74, v77, v76
	v_fmac_f32_e32 v77, v78, v75
	v_fma_f32 v74, -v74, v77, v76
	v_div_fmas_f32 v74, v74, v75, v77
	v_div_fixup_f32 v73, v74, v73, 1.0
	v_mul_f32_e32 v74, v30, v73
	v_mul_f32_e32 v73, 0xbfb8aa3b, v27
	v_exp_f32_e32 v75, v73
	v_or_b32_e32 v72, 34, v67
	v_lshlrev_b32_e32 v72, s4, v72
	v_add_u32_e32 v72, s42, v72
	v_add_f32_e32 v75, 1.0, v75
	v_div_scale_f32 v76, s[6:7], v75, v75, 1.0
	v_rcp_f32_e32 v77, v76
	v_ashrrev_i32_e32 v73, 31, v72
	v_lshlrev_b64 v[72:73], 10, v[72:73]
	v_lshl_add_u64 v[72:73], v[64:65], 0, v[72:73]
	v_fma_f32 v78, -v76, v77, 1.0
	v_fmac_f32_e32 v77, v78, v77
	v_div_scale_f32 v78, vcc, 1.0, v75, 1.0
	v_mul_f32_e32 v79, v78, v77
	v_fma_f32 v80, -v76, v79, v78
	v_fmac_f32_e32 v79, v80, v77
	v_fma_f32 v76, -v76, v79, v78
	v_div_fmas_f32 v76, v76, v77, v79
	v_div_fixup_f32 v75, v76, v75, 1.0
	v_mul_f32_e32 v76, v31, v75
	v_mul_f32_e32 v75, 0xbfb8aa3b, v16
	v_exp_f32_e32 v77, v75
	global_store_dword v[72:73], v74, off
	v_or_b32_e32 v74, 35, v67
	v_lshlrev_b32_e32 v74, s4, v74
	v_add_f32_e32 v77, 1.0, v77
	v_div_scale_f32 v78, s[6:7], v77, v77, 1.0
	v_add_u32_e32 v74, s42, v74
	v_rcp_f32_e32 v79, v78
	v_ashrrev_i32_e32 v75, 31, v74
	v_lshlrev_b64 v[74:75], 10, v[74:75]
	v_lshl_add_u64 v[74:75], v[64:65], 0, v[74:75]
	global_store_dword v[74:75], v76, off
	v_fma_f32 v76, -v78, v79, 1.0
	v_fmac_f32_e32 v79, v76, v79
	v_div_scale_f32 v76, vcc, 1.0, v77, 1.0
	v_mul_f32_e32 v80, v76, v79
	v_fma_f32 v81, -v78, v80, v76
	v_fmac_f32_e32 v80, v81, v79
	v_mul_f32_e32 v81, 0xbfb8aa3b, v17
	v_exp_f32_e32 v81, v81
	v_fma_f32 v76, -v78, v80, v76
	v_div_fmas_f32 v76, v76, v79, v80
	v_div_fixup_f32 v76, v76, v77, 1.0
	v_add_f32_e32 v78, 1.0, v81
	v_div_scale_f32 v79, s[6:7], v78, v78, 1.0
	v_rcp_f32_e32 v80, v79
	v_mul_f32_e32 v76, v20, v76
	global_store_dword v[68:69], v76, off offset:64
	v_fma_f32 v68, -v79, v80, 1.0
	v_fmac_f32_e32 v80, v68, v80
	v_div_scale_f32 v68, vcc, 1.0, v78, 1.0
	v_mul_f32_e32 v69, v68, v80
	v_fma_f32 v76, -v79, v69, v68
	v_fmac_f32_e32 v69, v76, v80
	v_mul_f32_e32 v76, 0xbfb8aa3b, v18
	v_exp_f32_e32 v76, v76
	v_fma_f32 v68, -v79, v69, v68
	v_div_fmas_f32 v68, v68, v80, v69
	v_div_fixup_f32 v68, v68, v78, 1.0
	v_add_f32_e32 v69, 1.0, v76
	v_div_scale_f32 v76, s[6:7], v69, v69, 1.0
	v_rcp_f32_e32 v77, v76
	v_mul_f32_e32 v68, v21, v68
	global_store_dword v[70:71], v68, off offset:64
	v_fma_f32 v68, -v76, v77, 1.0
	v_fmac_f32_e32 v77, v68, v77
	v_div_scale_f32 v68, vcc, 1.0, v69, 1.0
	v_mul_f32_e32 v70, v68, v77
	v_fma_f32 v71, -v76, v70, v68
	v_fmac_f32_e32 v70, v71, v77
	v_mul_f32_e32 v71, 0xbfb8aa3b, v19
	v_exp_f32_e32 v71, v71
	v_fma_f32 v68, -v76, v70, v68
	v_div_fmas_f32 v68, v68, v77, v70
; __device__ __forceinline__ float sigmoidf_(float v) { return 1.f / (1.f + __expf(-v)); }
; __device__ void phase_inproj(CParams& p, int l, int tm, int tn, char* smem) {
;     ...
;     int T = tn - 6;
;     const int lane = tid & 63, wid = tid >> 6, wr = wid >> 1, wc = wid & 1;
; #pragma unroll
;     for (int mi = 0; mi < 4; mi++)
; #pragma unroll
;       for (int a = 0; a < 2; a++)
; #pragma unroll
;         for (int j = 0; j < 4; j++) {
;           int rl = wr * 64 + mi * 16 + (lane >> 4) * 4 + j;
;           int ch = T * 64 + wc * 32 + a * 16 + (lane & 15);
;           float val = acc[mi][2 * a][j], gt = acc[mi][2 * a + 1][j];
;           p.zv[(size_t)(tbase + rl * tstr) * 256 + ch] = val * sigmoidf_(gt);
;         }
	v_div_fixup_f32 v68, v68, v69, 1.0
	v_add_f32_e32 v70, 1.0, v71
	v_div_scale_f32 v71, s[6:7], v70, v70, 1.0
	v_rcp_f32_e32 v76, v71
	v_mul_f32_e32 v68, v22, v68
	global_store_dword v[72:73], v68, off offset:64
	v_fma_f32 v68, -v71, v76, 1.0
	v_fmac_f32_e32 v76, v68, v76
	v_div_scale_f32 v68, vcc, 1.0, v70, 1.0
	v_mul_f32_e32 v69, v68, v76
	v_fma_f32 v72, -v71, v69, v68
	v_fmac_f32_e32 v69, v72, v76
	v_fma_f32 v68, -v71, v69, v68
	v_mul_f32_e32 v71, 0xbfb8aa3b, v4
	v_exp_f32_e32 v71, v71
	v_div_fmas_f32 v68, v68, v76, v69
	v_div_fixup_f32 v68, v68, v70, 1.0
	v_mul_f32_e32 v68, v23, v68
	v_add_f32_e32 v69, 1.0, v71
	v_div_scale_f32 v70, s[6:7], v69, v69, 1.0
	v_rcp_f32_e32 v71, v70
	global_store_dword v[74:75], v68, off offset:64
	v_or_b32_e32 v68, 48, v67
	v_lshlrev_b32_e32 v68, s4, v68
	v_fma_f32 v72, -v70, v71, 1.0
	v_fmac_f32_e32 v71, v72, v71
	v_div_scale_f32 v72, vcc, 1.0, v69, 1.0
	v_mul_f32_e32 v73, v72, v71
	v_fma_f32 v74, -v70, v73, v72
	v_fmac_f32_e32 v73, v74, v71
	v_fma_f32 v70, -v70, v73, v72
	v_div_fmas_f32 v70, v70, v71, v73
	v_div_fixup_f32 v69, v70, v69, 1.0
	v_mul_f32_e32 v70, v12, v69
	v_mul_f32_e32 v69, 0xbfb8aa3b, v5
	v_exp_f32_e32 v71, v69
	v_add_u32_e32 v68, s42, v68
	v_ashrrev_i32_e32 v69, 31, v68
	v_lshlrev_b64 v[68:69], 10, v[68:69]
	v_add_f32_e32 v71, 1.0, v71
	v_div_scale_f32 v72, s[6:7], v71, v71, 1.0
	v_rcp_f32_e32 v73, v72
	v_lshl_add_u64 v[68:69], v[64:65], 0, v[68:69]
	global_store_dword v[68:69], v70, off
	v_or_b32_e32 v70, 49, v67
	v_fma_f32 v74, -v72, v73, 1.0
	v_fmac_f32_e32 v73, v74, v73
	v_div_scale_f32 v74, vcc, 1.0, v71, 1.0
	v_mul_f32_e32 v75, v74, v73
	v_fma_f32 v76, -v72, v75, v74
	v_fmac_f32_e32 v75, v76, v73
	v_fma_f32 v72, -v72, v75, v74
	v_div_fmas_f32 v72, v72, v73, v75
	v_div_fixup_f32 v71, v72, v71, 1.0
	v_mul_f32_e32 v72, v13, v71
	v_mul_f32_e32 v71, 0xbfb8aa3b, v6
	v_exp_f32_e32 v73, v71
	v_lshlrev_b32_e32 v70, s4, v70
	v_add_u32_e32 v70, s42, v70
	v_ashrrev_i32_e32 v71, 31, v70
	v_add_f32_e32 v73, 1.0, v73
	v_div_scale_f32 v74, s[6:7], v73, v73, 1.0
	v_rcp_f32_e32 v75, v74
	v_lshlrev_b64 v[70:71], 10, v[70:71]
	v_lshl_add_u64 v[70:71], v[64:65], 0, v[70:71]
	global_store_dword v[70:71], v72, off
	v_fma_f32 v76, -v74, v75, 1.0
	v_fmac_f32_e32 v75, v76, v75
	v_div_scale_f32 v76, vcc, 1.0, v73, 1.0
	v_mul_f32_e32 v77, v76, v75
	v_fma_f32 v78, -v74, v77, v76
	v_fmac_f32_e32 v77, v78, v75
	v_fma_f32 v74, -v74, v77, v76
	v_div_fmas_f32 v74, v74, v75, v77
	v_div_fixup_f32 v73, v74, v73, 1.0
	v_mul_f32_e32 v74, v14, v73
	v_mul_f32_e32 v73, 0xbfb8aa3b, v7
	v_exp_f32_e32 v75, v73
	v_or_b32_e32 v72, 50, v67
	v_lshlrev_b32_e32 v72, s4, v72
	v_add_u32_e32 v72, s42, v72
	v_add_f32_e32 v75, 1.0, v75
	v_div_scale_f32 v76, s[6:7], v75, v75, 1.0
	v_rcp_f32_e32 v77, v76
	v_ashrrev_i32_e32 v73, 31, v72
	v_lshlrev_b64 v[72:73], 10, v[72:73]
	v_lshl_add_u64 v[72:73], v[64:65], 0, v[72:73]
	global_store_dword v[72:73], v74, off
	v_fma_f32 v74, -v76, v77, 1.0
	v_fmac_f32_e32 v77, v74, v77
	v_div_scale_f32 v74, vcc, 1.0, v75, 1.0
	v_mul_f32_e32 v78, v74, v77
	v_fma_f32 v79, -v76, v78, v74
	v_fmac_f32_e32 v78, v79, v77
	v_fma_f32 v74, -v76, v78, v74
	v_div_fmas_f32 v74, v74, v77, v78
	v_div_fixup_f32 v74, v74, v75, 1.0
	v_mul_f32_e32 v76, v15, v74
	v_mul_f32_e32 v74, 0xbfb8aa3b, v8
	v_exp_f32_e32 v77, v74
	v_or_b32_e32 v67, 51, v67
	v_lshlrev_b32_e32 v67, s4, v67
	v_add_u32_e32 v74, s42, v67
	v_add_f32_e32 v67, 1.0, v77
	v_div_scale_f32 v77, s[6:7], v67, v67, 1.0
	v_rcp_f32_e32 v78, v77
	v_ashrrev_i32_e32 v75, 31, v74
	v_lshlrev_b64 v[74:75], 10, v[74:75]
	v_lshl_add_u64 v[64:65], v[64:65], 0, v[74:75]
	v_fma_f32 v74, -v77, v78, 1.0
	v_fmac_f32_e32 v78, v74, v78
	v_div_scale_f32 v74, vcc, 1.0, v67, 1.0
	v_mul_f32_e32 v75, v74, v78
	global_store_dword v[64:65], v76, off
	v_fma_f32 v76, -v77, v75, v74
	v_fmac_f32_e32 v75, v76, v78
	v_mul_f32_e32 v76, 0xbfb8aa3b, v9
	v_exp_f32_e32 v76, v76
	v_fma_f32 v74, -v77, v75, v74
	v_div_fmas_f32 v74, v74, v78, v75
	v_div_fixup_f32 v67, v74, v67, 1.0
	v_add_f32_e32 v75, 1.0, v76
	v_div_scale_f32 v76, s[6:7], v75, v75, 1.0
	v_rcp_f32_e32 v77, v76
	v_mul_f32_e32 v67, v0, v67
	global_store_dword v[68:69], v67, off offset:64
	v_fma_f32 v67, -v76, v77, 1.0
	v_fmac_f32_e32 v77, v67, v77
	v_div_scale_f32 v67, vcc, 1.0, v75, 1.0
	v_mul_f32_e32 v68, v67, v77
	v_fma_f32 v69, -v76, v68, v67
	v_fmac_f32_e32 v68, v69, v77
	v_mul_f32_e32 v69, 0xbfb8aa3b, v10
	v_exp_f32_e32 v69, v69
	v_fma_f32 v67, -v76, v68, v67
	v_div_fmas_f32 v67, v67, v77, v68
	v_div_fixup_f32 v67, v67, v75, 1.0
	v_add_f32_e32 v68, 1.0, v69
	v_div_scale_f32 v69, s[6:7], v68, v68, 1.0
	v_rcp_f32_e32 v74, v69
	v_mul_f32_e32 v67, v1, v67
	global_store_dword v[70:71], v67, off offset:64
	v_fma_f32 v67, -v69, v74, 1.0
	v_fmac_f32_e32 v74, v67, v74
	v_div_scale_f32 v67, vcc, 1.0, v68, 1.0
	v_mul_f32_e32 v70, v67, v74
	v_fma_f32 v71, -v69, v70, v67
	v_fmac_f32_e32 v70, v71, v74
	v_mul_f32_e32 v71, 0xbfb8aa3b, v11
	v_exp_f32_e32 v71, v71
	v_fma_f32 v67, -v69, v70, v67
	v_div_fmas_f32 v67, v67, v74, v70
	v_div_fixup_f32 v67, v67, v68, 1.0
	v_add_f32_e32 v69, 1.0, v71
	v_div_scale_f32 v70, s[6:7], v69, v69, 1.0
	v_rcp_f32_e32 v71, v70
	v_mul_f32_e32 v67, v2, v67
	global_store_dword v[72:73], v67, off offset:64
	v_fma_f32 v67, -v70, v71, 1.0
	v_fmac_f32_e32 v71, v67, v71
	v_div_scale_f32 v67, vcc, 1.0, v69, 1.0
	v_mul_f32_e32 v68, v67, v71
	v_fma_f32 v72, -v70, v68, v67
	v_fmac_f32_e32 v68, v72, v71
	v_fma_f32 v67, -v70, v68, v67
	v_div_fmas_f32 v67, v67, v71, v68
	v_div_fixup_f32 v67, v67, v69, 1.0
	v_mul_f32_e32 v67, v3, v67
	global_store_dword v[64:65], v67, off offset:64

; __global__ void __launch_bounds__(256, 2) fwd_megakernel(Params p_unused) {
;     ...
;   __shared__ __attribute__((aligned(16))) char smem[SMEM_BYTES];
	.amdhsa_kernel _Z14fwd_megakernel6Params
		.amdhsa_group_segment_fixed_size 74752
		.amdhsa_private_segment_fixed_size 0
		.amdhsa_kernarg_size 808
		.amdhsa_user_sgpr_count 2
		.amdhsa_user_sgpr_dispatch_ptr 0
		.amdhsa_user_sgpr_queue_ptr 0
		.amdhsa_user_sgpr_kernarg_segment_ptr 1
		.amdhsa_user_sgpr_dispatch_id 0
		.amdhsa_user_sgpr_kernarg_preload_length 0
		.amdhsa_user_sgpr_kernarg_preload_offset 0
		.amdhsa_user_sgpr_private_segment_size 0
		.amdhsa_uses_dynamic_stack 0
		.amdhsa_enable_private_segment 0
		.amdhsa_system_sgpr_workgroup_id_x 1
		.amdhsa_system_sgpr_workgroup_id_y 0
		.amdhsa_system_sgpr_workgroup_id_z 0
		.amdhsa_system_sgpr_workgroup_info 0
		.amdhsa_system_vgpr_workitem_id 2
		.amdhsa_next_free_vgpr 256
		.amdhsa_next_free_sgpr 100
		.amdhsa_accum_offset 256
		.amdhsa_reserve_vcc 1
		.amdhsa_float_round_mode_32 0
		.amdhsa_float_round_mode_16_64 0
		.amdhsa_float_denorm_mode_32 3
		.amdhsa_float_denorm_mode_16_64 3
		.amdhsa_dx10_clamp 1
		.amdhsa_ieee_mode 1
		.amdhsa_fp16_overflow 0
		.amdhsa_tg_split 0
		.amdhsa_exception_fp_ieee_invalid_op 0
		.amdhsa_exception_fp_denorm_src 0
		.amdhsa_exception_fp_ieee_div_zero 0
		.amdhsa_exception_fp_ieee_overflow 0
		.amdhsa_exception_fp_ieee_underflow 0
		.amdhsa_exception_fp_ieee_inexact 0
		.amdhsa_exception_int_div_zero 0
	.end_amdhsa_kernel

; __global__ void __launch_bounds__(256, 2) fwd_megakernel(Params p_unused) {
;     ...
;   __shared__ __attribute__((aligned(16))) char smem[SMEM_BYTES];
amdhsa.kernels:
  - .agpr_count:     0
    .args:
      - .offset:         0
        .size:           552
        .value_kind:     by_value
      - .offset:         552
        .size:           4
        .value_kind:     hidden_block_count_x
      - .offset:         556
        .size:           4
        .value_kind:     hidden_block_count_y
      - .offset:         560
        .size:           4
        .value_kind:     hidden_block_count_z
      - .offset:         564
        .size:           2
        .value_kind:     hidden_group_size_x
      - .offset:         566
        .size:           2
        .value_kind:     hidden_group_size_y
      - .offset:         568
        .size:           2
        .value_kind:     hidden_group_size_z
      - .offset:         570
        .size:           2
        .value_kind:     hidden_remainder_x
      - .offset:         572
        .size:           2
        .value_kind:     hidden_remainder_y
      - .offset:         574
        .size:           2
        .value_kind:     hidden_remainder_z
      - .offset:         592
        .size:           8
        .value_kind:     hidden_global_offset_x
      - .offset:         600
        .size:           8
        .value_kind:     hidden_global_offset_y
      - .offset:         608
        .size:           8
        .value_kind:     hidden_global_offset_z
      - .offset:         616
        .size:           2
        .value_kind:     hidden_grid_dims
      - .offset:         640
        .size:           8
        .value_kind:     hidden_multigrid_sync_arg
    .group_segment_fixed_size: 74752
    .kernarg_segment_align: 8
    .kernarg_segment_size: 808
    .language:       OpenCL C
    .language_version:
      - 2
      - 0
    .max_flat_workgroup_size: 256
    .name:           _Z14fwd_megakernel6Params
    .private_segment_fixed_size: 0
    .sgpr_count:     106
    .sgpr_spill_count: 120
    .symbol:         _Z14fwd_megakernel6Params.kd
    .uniform_work_group_size: 1
    .uses_dynamic_stack: false
    .vgpr_count:     256
    .vgpr_spill_count: 0
    .wavefront_size: 64
